# grid barrier: the per-CU L1 invalidate (buffer_inv sc1) issued right after the arrival atomic and overlapped with the wait for the other workgroups, instead of after the release
# speedup vs baseline: 1.0148x; 1.0148x over previous
.LBB0_90:
	v_readlane_b32 s4, v254, 5
	s_lshl_b32 s4, s4, 8
	v_readlane_b32 s6, v254, 3
	v_readlane_b32 s7, v254, 4
	s_add_u32 s4, s6, s4
	s_addc_u32 s5, s7, 0
	v_mov_b32_e32 v1, 0x1000
	v_mov_b32_e32 v3, 1
	global_atomic_add v3, v1, v3, s[4:5] offset:1024 sc0
	buffer_inv sc1
	v_cvt_f32_u32_e32 v1, v2
	v_sub_u32_e32 v4, 0, v2
	v_rcp_iflag_f32_e32 v1, v1
	s_nop 0
	v_mul_f32_e32 v1, 0x4f7ffffe, v1
	v_cvt_u32_f32_e32 v1, v1
	v_mul_lo_u32 v4, v4, v1
	v_mul_hi_u32 v4, v1, v4
	v_add_u32_e32 v1, v1, v4
	s_waitcnt vmcnt(1)
	v_mul_hi_u32 v1, v3, v1
	v_mul_lo_u32 v4, v1, v2
	v_sub_u32_e32 v4, v3, v4
	v_add_u32_e32 v5, 1, v1
	v_cmp_ge_u32_e32 vcc, v4, v2
	v_add_u32_e32 v3, 1, v3
	s_nop 0
	v_cndmask_b32_e32 v1, v1, v5, vcc
	v_sub_u32_e32 v5, v4, v2
	v_cndmask_b32_e32 v4, v4, v5, vcc
	v_add_u32_e32 v5, 1, v1
	v_cmp_ge_u32_e32 vcc, v4, v2
	s_nop 1
	v_cndmask_b32_e32 v1, v1, v5, vcc
	v_mul_lo_u32 v4, v2, v1
	v_add_u32_e32 v2, v4, v2
	v_cmp_ne_u32_e32 vcc, v3, v2
	s_and_saveexec_b64 s[6:7], vcc
	s_xor_b64 s[6:7], exec, s[6:7]
	s_cbranch_execz .LBB0_104
	s_waitcnt lgkmcnt(0)
	v_mov_b32_e32 v0, 0x2000
	global_load_dword v0, v0, s[4:5] offset:1024 sc1
	s_add_u32 s12, s4, 0x2400
	s_addc_u32 s13, s5, 0
	s_waitcnt vmcnt(0)
	v_cmp_eq_u32_e32 vcc, v0, v1
	s_and_saveexec_b64 s[8:9], vcc
	s_cbranch_execz .LBB0_103
	s_add_u32 s10, s28, 0x4200
	s_addc_u32 s11, s29, 0
	s_mov_b32 s56, 1
	s_mov_b64 s[14:15], 0
	v_mov_b32_e32 v0, 0
	s_branch .LBB0_94

.LBB0_103:
	s_or_b64 exec, exec, s[8:9]
	s_waitcnt vmcnt(0)
	s_nop 0
	s_waitcnt vmcnt(0)

.LBB0_121:
	s_or_b64 exec, exec, s[6:7]
	v_mov_b32_e32 v0, 0x2000
	v_mov_b32_e32 v1, 1
	s_waitcnt vmcnt(0)
	s_nop 0
	global_atomic_add v0, v1, s[4:5] offset:1024
	s_waitcnt vmcnt(0)

.LBB0_312:
	v_readlane_b32 s4, v254, 5
	s_lshl_b32 s4, s4, 8
	v_readlane_b32 s6, v254, 3
	v_readlane_b32 s7, v254, 4
	s_add_u32 s4, s6, s4
	s_addc_u32 s5, s7, 0
	v_mov_b32_e32 v1, 0x1000
	v_mov_b32_e32 v3, 1
	global_atomic_add v3, v1, v3, s[4:5] offset:1024 sc0
	buffer_inv sc1
	v_cvt_f32_u32_e32 v1, v2
	v_sub_u32_e32 v4, 0, v2
	v_rcp_iflag_f32_e32 v1, v1
	s_nop 0
	v_mul_f32_e32 v1, 0x4f7ffffe, v1
	v_cvt_u32_f32_e32 v1, v1
	v_mul_lo_u32 v4, v4, v1
	v_mul_hi_u32 v4, v1, v4
	v_add_u32_e32 v1, v1, v4
	s_waitcnt vmcnt(1)
	v_mul_hi_u32 v1, v3, v1
	v_mul_lo_u32 v4, v1, v2
	v_sub_u32_e32 v4, v3, v4
	v_add_u32_e32 v5, 1, v1
	v_cmp_ge_u32_e32 vcc, v4, v2
	v_add_u32_e32 v3, 1, v3
	s_nop 0
	v_cndmask_b32_e32 v1, v1, v5, vcc
	v_sub_u32_e32 v5, v4, v2
	v_cndmask_b32_e32 v4, v4, v5, vcc
	v_add_u32_e32 v5, 1, v1
	v_cmp_ge_u32_e32 vcc, v4, v2
	s_nop 1
	v_cndmask_b32_e32 v1, v1, v5, vcc
	v_mul_lo_u32 v4, v2, v1
	v_add_u32_e32 v2, v4, v2
	v_cmp_ne_u32_e32 vcc, v3, v2
	s_and_saveexec_b64 s[6:7], vcc
	s_xor_b64 s[6:7], exec, s[6:7]
	s_cbranch_execz .LBB0_326
	s_waitcnt lgkmcnt(0)
	v_mov_b32_e32 v0, 0x2000
	global_load_dword v0, v0, s[4:5] offset:1024 sc1
	s_add_u32 s12, s4, 0x2400
	s_addc_u32 s13, s5, 0
	s_waitcnt vmcnt(0)
	v_cmp_eq_u32_e32 vcc, v0, v1
	s_and_saveexec_b64 s[8:9], vcc
	s_cbranch_execz .LBB0_325
	s_add_u32 s10, s28, 0x4200
	s_addc_u32 s11, s29, 0
	s_mov_b32 s40, 1
	s_mov_b64 s[14:15], 0
	v_mov_b32_e32 v0, 0
	s_branch .LBB0_316

.LBB0_1117:
	v_readlane_b32 s4, v254, 5
	s_lshl_b32 s4, s4, 8
	v_readlane_b32 s6, v254, 3
	v_readlane_b32 s7, v254, 4
	s_add_u32 s4, s6, s4
	s_addc_u32 s5, s7, 0
	v_mov_b32_e32 v1, 0x1000
	v_mov_b32_e32 v3, 1
	global_atomic_add v3, v1, v3, s[4:5] offset:1024 sc0
	buffer_inv sc1
	v_cvt_f32_u32_e32 v1, v2
	v_sub_u32_e32 v4, 0, v2
	v_rcp_iflag_f32_e32 v1, v1
	s_nop 0
	v_mul_f32_e32 v1, 0x4f7ffffe, v1
	v_cvt_u32_f32_e32 v1, v1
	v_mul_lo_u32 v4, v4, v1
	v_mul_hi_u32 v4, v1, v4
	v_add_u32_e32 v1, v1, v4
	s_waitcnt vmcnt(1)
	v_mul_hi_u32 v1, v3, v1
	v_mul_lo_u32 v4, v1, v2
	v_sub_u32_e32 v4, v3, v4
	v_add_u32_e32 v5, 1, v1
	v_cmp_ge_u32_e32 vcc, v4, v2
	v_add_u32_e32 v3, 1, v3
	s_nop 0
	v_cndmask_b32_e32 v1, v1, v5, vcc
	v_sub_u32_e32 v5, v4, v2
	v_cndmask_b32_e32 v4, v4, v5, vcc
	v_add_u32_e32 v5, 1, v1
	v_cmp_ge_u32_e32 vcc, v4, v2
	s_nop 1
	v_cndmask_b32_e32 v1, v1, v5, vcc
	v_mul_lo_u32 v4, v2, v1
	v_add_u32_e32 v2, v4, v2
	v_cmp_ne_u32_e32 vcc, v3, v2
	s_and_saveexec_b64 s[6:7], vcc
	s_xor_b64 s[6:7], exec, s[6:7]
	s_cbranch_execz .LBB0_1131
	s_waitcnt lgkmcnt(0)
	v_mov_b32_e32 v0, 0x2000
	global_load_dword v0, v0, s[4:5] offset:1024 sc1
	s_add_u32 s14, s4, 0x2400
	s_addc_u32 s15, s5, 0
	s_waitcnt vmcnt(0)
	v_cmp_eq_u32_e32 vcc, v0, v1
	s_and_saveexec_b64 s[10:11], vcc
	s_cbranch_execz .LBB0_1130
	s_add_u32 s12, s28, 0x4200
	s_addc_u32 s13, s29, 0
	s_mov_b32 s40, 1
	s_mov_b64 s[18:19], 0
	v_mov_b32_e32 v0, 0
	s_branch .LBB0_1121

.LBB0_1130:
	s_or_b64 exec, exec, s[10:11]
	s_waitcnt vmcnt(0)
	s_nop 0
	s_waitcnt vmcnt(0)

.LBB0_1825:
	v_readlane_b32 s4, v254, 5
	s_lshl_b32 s4, s4, 8
	v_readlane_b32 s6, v254, 3
	v_readlane_b32 s7, v254, 4
	s_add_u32 s4, s6, s4
	s_addc_u32 s5, s7, 0
	v_mov_b32_e32 v1, 0x1000
	v_mov_b32_e32 v3, 1
	global_atomic_add v3, v1, v3, s[4:5] offset:1024 sc0
	buffer_inv sc1
	v_cvt_f32_u32_e32 v1, v2
	v_sub_u32_e32 v4, 0, v2
	v_rcp_iflag_f32_e32 v1, v1
	s_nop 0
	v_mul_f32_e32 v1, 0x4f7ffffe, v1
	v_cvt_u32_f32_e32 v1, v1
	v_mul_lo_u32 v4, v4, v1
	v_mul_hi_u32 v4, v1, v4
	v_add_u32_e32 v1, v1, v4
	s_waitcnt vmcnt(1)
	v_mul_hi_u32 v1, v3, v1
	v_mul_lo_u32 v4, v1, v2
	v_sub_u32_e32 v4, v3, v4
	v_add_u32_e32 v5, 1, v1
	v_cmp_ge_u32_e32 vcc, v4, v2
	v_add_u32_e32 v3, 1, v3
	s_nop 0
	v_cndmask_b32_e32 v1, v1, v5, vcc
	v_sub_u32_e32 v5, v4, v2
	v_cndmask_b32_e32 v4, v4, v5, vcc
	v_add_u32_e32 v5, 1, v1
	v_cmp_ge_u32_e32 vcc, v4, v2
	s_nop 1
	v_cndmask_b32_e32 v1, v1, v5, vcc
	v_mul_lo_u32 v4, v2, v1
	v_add_u32_e32 v2, v4, v2
	v_cmp_ne_u32_e32 vcc, v3, v2
	s_and_saveexec_b64 s[6:7], vcc
	s_xor_b64 s[6:7], exec, s[6:7]
	s_cbranch_execz .LBB0_1839
	s_waitcnt lgkmcnt(0)
	v_mov_b32_e32 v0, 0x2000
	global_load_dword v0, v0, s[4:5] offset:1024 sc1
	s_add_u32 s12, s4, 0x2400
	s_addc_u32 s13, s5, 0
	s_waitcnt vmcnt(0)
	v_cmp_eq_u32_e32 vcc, v0, v1
	s_and_saveexec_b64 s[8:9], vcc
	s_cbranch_execz .LBB0_1838
	s_add_u32 s10, s28, 0x4200
	s_addc_u32 s11, s29, 0
	s_mov_b32 s31, 1
	s_mov_b64 s[14:15], 0
	v_mov_b32_e32 v0, 0
	s_branch .LBB0_1829
